# adds: prefetch of the next weight tile in the phase-0 w_in_a transpose loop; phase-5 LayerNorm with hoisted gamma/beta and next-row prefetch
# speedup vs baseline: 1.0179x; 1.0058x over previous
; DI void conv_tile(float* tile, bf16_t* dst, int Kdim, const float* src, int ld, int n0, int k0, int sc0, int nvalid) {
;     const int tid = threadIdx.x;
; #pragma unroll
;     for (int it = 0; it < 2; ++it) {
;         const int idx = tid + 512 * it, kk = idx >> 4, c4 = (idx & 15) * 4;
;         f32x4 v = (f32x4){0.f, 0.f, 0.f, 0.f};
;         if (c4 < nvalid) v = *(const f32x4*)(src + (size_t)(k0 + kk) * ld + sc0 + c4);
;         float* tp = tile + kk * 65 + c4; tp[0] = v[0]; tp[1] = v[1]; tp[2] = v[2]; tp[3] = v[3];
;     }
;     __syncthreads();
; __device__ void phase_prep(const Params& p, unsigned char* shm) {
;     ...
;     for (int t = b; t < 192 * 32; t += nb) {
;         const int nblk = t >> 5, kb = t & 31, n0 = nblk * 64, pn = n0 >> 8, j = n0 & 255;
;         const int sc0 = (pn < 32) ? (((j >> 7) ? 8192 : 0) + pn * 128 + (j & 127)) : (4096 + (n0 - 8192));
;         conv_tile(tile, WINA, 2048, p.in[2], 12288, n0, kb * 64, sc0, 64);
;     }
.LBB0_84:
	s_or_b64 exec, exec, s[4:5]
	v_lshlrev_b32_e32 v0, 2, v136
	v_add_u32_e32 v3, 0x200, v136
	v_lshlrev_b32_e32 v4, 3, v136
	v_and_b32_e32 v0, 60, v0
	v_lshrrev_b32_e32 v8, 4, v136
	v_lshrrev_b32_e32 v9, 4, v3
	v_lshrrev_b32_e32 v10, 3, v136
	v_and_b32_e32 v4, 56, v4
	v_lshl_add_u32 v1, v0, 2, 0
	v_mul_u32_u24_e32 v2, 0x104, v8
	v_mul_u32_u24_e32 v3, 0x104, v9
	v_mul_u32_u24_e32 v6, 0x104, v4
	v_lshlrev_b32_e32 v7, 2, v10
	s_cmpk_gt_i32 s2, 0x17ff
	s_mov_b32 s5, 0
	v_mov_b32_e32 v5, 0
	v_add3_u32 v11, 0, v6, v7
	v_add_u32_e32 v12, v1, v2
	v_add_u32_e32 v13, v1, v3
	v_lshlrev_b32_e32 v0, 2, v0
	v_lshlrev_b32_e32 v2, 1, v4
	s_cbranch_scc1 .LBB0_91
	s_add_u32 s6, s26, 0x32000000
	v_mov_b32_e32 v1, v5
	s_addc_u32 s7, s27, 0
	v_lshl_add_u64 v[6:7], s[8:9], 0, v[0:1]
	s_lshl_b32 s0, s2, 7
	s_lshl_b32 s1, s30, 7
	s_lshl_b32 s3, s2, 6
	s_lshl_b32 s22, s30, 6
	s_lshl_b32 s23, s2, 1
	s_lshl_b32 s24, s30, 1
	v_mov_b32_e32 v3, v5
	v_add_u32_e32 v1, 0x400, v11
	s_mov_b32 s25, s2
	s_and_b32 s4, s23, 0xffffffc0
	s_cmpk_gt_i32 s25, 0xfff
	s_cbranch_scc0 .Lc0_lo_p
	s_add_i32 s8, s4, 0xfffff000
	s_branch .Lc0_ld_p
.Lc0_lo_p:
	s_and_b32 s8, s0, 0x2000
	s_and_b32 s9, s25, 0xffffff80
	s_add_i32 s8, s8, s9
	s_and_b32 s9, s23, 64
	s_or_b32 s8, s8, s9
.Lc0_ld_p:
	s_and_b32 s14, s3, 0x7c0
	s_ashr_i32 s9, s8, 31
	v_or_b32_e32 v4, s14, v8
	v_lshl_add_u64 v[18:19], s[8:9], 2, v[6:7]
	v_mul_u32_u24_e32 v4, 0x3000, v4
	v_lshl_add_u64 v[14:15], v[4:5], 2, v[18:19]
	v_add_u32_e32 v4, s14, v9
	global_load_dwordx4 v[30:33], v[14:15], off
	v_mul_u32_u24_e32 v4, 0x3000, v4
	v_lshl_add_u64 v[18:19], v[4:5], 2, v[18:19]
	global_load_dwordx4 v[34:37], v[18:19], off
	v_add_u32_e32 v38, s4, v10
	v_ashrrev_i32_e32 v39, 31, v38
	v_lshlrev_b64 v[38:39], 12, v[38:39]
	s_lshl_b32 s4, s14, 1
	v_lshl_add_u64 v[38:39], s[6:7], 0, v[38:39]
	s_add_i32 s25, s25, s30
	s_add_i32 s0, s0, s1
	s_add_i32 s3, s3, s22
	s_add_i32 s23, s23, s24
	v_lshl_add_u64 v[38:39], v[38:39], 0, s[4:5]
	v_lshl_add_u64 v[38:39], v[38:39], 0, v[2:3]
	s_cmpk_gt_i32 s25, 0x17ff
	s_cselect_b64 s[98:99], -1, 0
	s_waitcnt vmcnt(0)
.Lc0_loop:
	s_waitcnt vmcnt(1)
	ds_write2_b32 v12, v30, v31 offset1:1
	ds_write2_b32 v12, v32, v33 offset0:2 offset1:3
	ds_write2_b32 v13, v34, v35 offset1:1
	ds_write2_b32 v13, v36, v37 offset0:2 offset1:3
	s_waitcnt lgkmcnt(0)
	s_barrier
	v_mov_b64 v[22:23], v[38:39]
	s_mov_b64 s[100:101], s[98:99]
	s_and_b64 vcc, exec, s[98:99]
	s_cbranch_vccnz .Lc0_nonext
	s_and_b32 s4, s23, 0xffffffc0
	s_cmpk_gt_i32 s25, 0xfff
	s_cbranch_scc0 .Lc0_lo_l
	s_add_i32 s8, s4, 0xfffff000
	s_branch .Lc0_ld_l

; DI unsigned cvt_pk_bf16(float lo, float hi) { unsigned r; asm("v_cvt_pk_bf16_f32 %0, %1, %2" : "=v"(r) : "v"(lo), "v"(hi)); return r; }
; DI void conv_tile(float* tile, bf16_t* dst, int Kdim, const float* src, int ld, int n0, int k0, int sc0, int nvalid) {
;     const int tid = threadIdx.x;
; #pragma unroll
;     for (int it = 0; it < 2; ++it) {
;         const int idx = tid + 512 * it, kk = idx >> 4, c4 = (idx & 15) * 4;
;         f32x4 v = (f32x4){0.f, 0.f, 0.f, 0.f};
;         if (c4 < nvalid) v = *(const f32x4*)(src + (size_t)(k0 + kk) * ld + sc0 + c4);
;         float* tp = tile + kk * 65 + c4; tp[0] = v[0]; tp[1] = v[1]; tp[2] = v[2]; tp[3] = v[3];
;     }
;     __syncthreads();
;     { const int n = tid >> 3, k8 = (tid & 7) * 8; const float* tp = tile + k8 * 65 + n;
;       u32x4 w; w.x = cvt_pk_bf16(tp[0], tp[65]); w.y = cvt_pk_bf16(tp[130], tp[195]); w.z = cvt_pk_bf16(tp[260], tp[325]); w.w = cvt_pk_bf16(tp[390], tp[455]);
;       *(u32x4*)(dst + (size_t)(n0 + n) * Kdim + k0 + k8) = w; }
;     __syncthreads();
; }
.Lc0_ld_l:
	s_and_b32 s14, s3, 0x7c0
	s_ashr_i32 s9, s8, 31
	v_or_b32_e32 v4, s14, v8
	v_lshl_add_u64 v[18:19], s[8:9], 2, v[6:7]
	v_mul_u32_u24_e32 v4, 0x3000, v4
	v_lshl_add_u64 v[14:15], v[4:5], 2, v[18:19]
	v_add_u32_e32 v4, s14, v9
	global_load_dwordx4 v[30:33], v[14:15], off
	v_mul_u32_u24_e32 v4, 0x3000, v4
	v_lshl_add_u64 v[18:19], v[4:5], 2, v[18:19]
	global_load_dwordx4 v[34:37], v[18:19], off
	v_add_u32_e32 v38, s4, v10
	v_ashrrev_i32_e32 v39, 31, v38
	v_lshlrev_b64 v[38:39], 12, v[38:39]
	s_lshl_b32 s4, s14, 1
	v_lshl_add_u64 v[38:39], s[6:7], 0, v[38:39]
	s_add_i32 s25, s25, s30
	s_add_i32 s0, s0, s1
	s_add_i32 s3, s3, s22
	s_add_i32 s23, s23, s24
	v_lshl_add_u64 v[38:39], v[38:39], 0, s[4:5]
	v_lshl_add_u64 v[38:39], v[38:39], 0, v[2:3]
	s_cmpk_gt_i32 s25, 0x17ff
	s_cselect_b64 s[98:99], -1, 0
.Lc0_nonext:
	ds_read2_b32 v[14:15], v11 offset1:65
	ds_read2_b32 v[16:17], v11 offset0:130 offset1:195
	ds_read2_b32 v[18:19], v1 offset0:4 offset1:69
	ds_read2_b32 v[20:21], v1 offset0:134 offset1:199
	s_waitcnt lgkmcnt(3)
	v_cvt_pk_bf16_f32 v14, v14, v15
	s_waitcnt lgkmcnt(2)
	v_cvt_pk_bf16_f32 v15, v16, v17
	s_waitcnt lgkmcnt(1)
	v_cvt_pk_bf16_f32 v16, v18, v19
	s_waitcnt lgkmcnt(0)
	v_cvt_pk_bf16_f32 v17, v20, v21
	global_store_dwordx4 v[22:23], v[14:17], off
	s_barrier
	s_and_b64 vcc, exec, s[100:101]
	s_cbranch_vccz .Lc0_loop

; template <int MODE> __device__ void phase_ln(const bf16_t* src, void* dst, const float* gam, const float* bet) {
;     const int lane = threadIdx.x & 63, wid = threadIdx.x >> 6;
;     for (int row = blockIdx.x * 8 + wid; row < T; row += gridDim.x * 8) {
;         float x[32];
; #pragma unroll
;         for (int it = 0; it < 4; ++it) { const u32x4 w = *(const u32x4*)(src + (size_t)row * DM + it * 512 + lane * 8);
;             x[it * 8 + 0] = bflo(w.x); x[it * 8 + 1] = bfhi(w.x); x[it * 8 + 2] = bflo(w.y); x[it * 8 + 3] = bfhi(w.y);
;             x[it * 8 + 4] = bflo(w.z); x[it * 8 + 5] = bfhi(w.z); x[it * 8 + 6] = bflo(w.w); x[it * 8 + 7] = bfhi(w.w); }
;     ...
;         for (int it = 0; it < 4; ++it) {
;             const int col = it * 512 + lane * 8;
;             const f32x4 g0 = *(const f32x4*)(gam + col), g1 = *(const f32x4*)(gam + col + 4), b0 = *(const f32x4*)(bet + col), b1 = *(const f32x4*)(bet + col + 4);
.LBB0_420:
	v_lshrrev_b32_e32 v0, 6, v136
	v_lshl_add_u32 v0, s2, 3, v0
	s_mov_b32 s0, 0xa000
	v_cmp_gt_i32_e32 vcc, s0, v0
	v_lshlrev_b32_e32 v20, 3, v136
	s_and_saveexec_b64 s[6:7], vcc
	s_cbranch_execz .LBB0_423
	v_and_b32_e32 v1, 0x1f8, v20
	v_lshlrev_b32_e32 v16, 1, v1
	v_lshlrev_b32_e32 v12, 2, v1
	v_mbcnt_lo_u32_b32 v1, -1, 0
	v_mbcnt_hi_u32_b32 v1, -1, v1
	v_and_b32_e32 v18, 64, v1
	v_add_u32_e32 v18, 64, v18
	v_xor_b32_e32 v19, 32, v1
	v_cmp_lt_i32_e32 vcc, v19, v18
	v_mov_b32_e32 v17, 0
	v_lshl_add_u64 v[2:3], s[26:27], 0, v[16:17]
	v_cndmask_b32_e32 v19, v1, v19, vcc
	v_lshlrev_b32_e32 v21, 2, v19
	v_xor_b32_e32 v19, 16, v1
	v_cmp_lt_i32_e32 vcc, v19, v18
	s_mov_b64 s[0:1], 0x14000000
	s_waitcnt lgkmcnt(0)
	v_mov_b32_e32 v13, v17
	v_cndmask_b32_e32 v19, v1, v19, vcc
	v_lshlrev_b32_e32 v22, 2, v19
	v_xor_b32_e32 v19, 8, v1
	v_cmp_lt_i32_e32 vcc, v19, v18
	v_or_b32_e32 v10, 0x1000, v12
	v_mov_b32_e32 v11, v17
	v_cndmask_b32_e32 v19, v1, v19, vcc
	v_lshlrev_b32_e32 v23, 2, v19
	v_xor_b32_e32 v19, 4, v1
	v_cmp_lt_i32_e32 vcc, v19, v18
	v_or_b32_e32 v14, 0x1800, v12
	v_mov_b32_e32 v15, v17
	v_cndmask_b32_e32 v19, v1, v19, vcc
	v_lshlrev_b32_e32 v24, 2, v19
	v_xor_b32_e32 v19, 2, v1
	v_cmp_lt_i32_e32 vcc, v19, v18
	v_lshl_add_u64 v[2:3], v[2:3], 0, s[0:1]
	v_lshl_add_u64 v[4:5], s[46:47], 0, v[12:13]
	v_cndmask_b32_e32 v19, v1, v19, vcc
	v_lshlrev_b32_e32 v25, 2, v19
	v_xor_b32_e32 v19, 1, v1
	v_cmp_lt_i32_e32 vcc, v19, v18
	v_lshl_add_u64 v[6:7], s[48:49], 0, v[12:13]
	v_lshl_add_u64 v[8:9], s[46:47], 0, v[10:11]
	v_cndmask_b32_e32 v1, v1, v19, vcc
	v_lshl_add_u64 v[10:11], s[48:49], 0, v[10:11]
	v_lshl_add_u64 v[12:13], s[46:47], 0, v[14:15]
	v_lshl_add_u64 v[14:15], s[48:49], 0, v[14:15]
	s_lshl_b32 s0, s30, 3
	v_lshlrev_b32_e32 v26, 2, v1
	v_lshl_add_u64 v[16:17], s[50:51], 0, v[16:17]
	s_mov_b64 s[8:9], 0
	v_mov_b32_e32 v27, 0x3727c5ac
	s_mov_b32 s1, 0x800000
	s_mov_b32 s3, 0x9fff
	v_ashrrev_i32_e32 v1, 31, v0
	v_lshlrev_b64 v[18:19], 12, v[0:1]
	v_lshl_add_u64 v[44:45], v[2:3], 0, v[18:19]
	global_load_dwordx4 v[214:217], v[44:45], off
	global_load_dwordx4 v[218:221], v[44:45], off offset:1024
	global_load_dwordx4 v[222:225], v[44:45], off offset:2048
	global_load_dwordx4 v[226:229], v[44:45], off offset:3072
	global_load_dwordx4 v[150:153], v[4:5], off offset:16
	global_load_dwordx4 v[154:157], v[4:5], off
	global_load_dwordx4 v[158:161], v[6:7], off offset:16
	global_load_dwordx4 v[162:165], v[6:7], off
	global_load_dwordx4 v[166:169], v[4:5], off offset:2064
	global_load_dwordx4 v[170:173], v[4:5], off offset:2048
	global_load_dwordx4 v[174:177], v[6:7], off offset:2048
	global_load_dwordx4 v[178:181], v[6:7], off offset:2064
	global_load_dwordx4 v[182:185], v[8:9], off offset:16
	global_load_dwordx4 v[186:189], v[8:9], off
	global_load_dwordx4 v[190:193], v[10:11], off
	global_load_dwordx4 v[194:197], v[10:11], off offset:16
	global_load_dwordx4 v[198:201], v[12:13], off offset:16
	global_load_dwordx4 v[202:205], v[12:13], off
	global_load_dwordx4 v[206:209], v[14:15], off
	global_load_dwordx4 v[210:213], v[14:15], off offset:16
	s_waitcnt vmcnt(0)
.LBB0_422:
	s_waitcnt vmcnt(4)
	v_mov_b64 v[28:29], v[214:215]
	v_mov_b64 v[30:31], v[216:217]
	v_mov_b64 v[32:33], v[218:219]
	v_mov_b64 v[34:35], v[220:221]
	v_mov_b64 v[36:37], v[222:223]
	v_mov_b64 v[38:39], v[224:225]
	v_mov_b64 v[40:41], v[226:227]
	v_mov_b64 v[42:43], v[228:229]
	v_ashrrev_i32_e32 v1, 31, v0
	v_lshlrev_b64 v[18:19], 12, v[0:1]
	v_lshl_add_u64 v[18:19], v[16:17], 0, v[18:19]
	v_add_u32_e32 v0, s0, v0
	v_mov_b32_e32 v230, v0
	v_ashrrev_i32_e32 v231, 31, v0
	v_lshlrev_b64 v[230:231], 12, v[230:231]
	v_lshl_add_u64 v[230:231], v[2:3], 0, v[230:231]
	global_load_dwordx4 v[214:217], v[230:231], off
	global_load_dwordx4 v[218:221], v[230:231], off offset:1024
	global_load_dwordx4 v[222:225], v[230:231], off offset:2048
	global_load_dwordx4 v[226:229], v[230:231], off offset:3072
	v_lshlrev_b32_e32 v1, 16, v28
	v_and_b32_e32 v52, 0xffff0000, v28
	v_add_f32_e32 v28, 0, v1
	v_lshlrev_b32_e32 v53, 16, v29
	v_add_f32_e32 v28, v28, v52
	v_and_b32_e32 v54, 0xffff0000, v29
	v_add_f32_e32 v28, v28, v53
	v_lshlrev_b32_e32 v55, 16, v30
	v_add_f32_e32 v28, v28, v54
	v_and_b32_e32 v56, 0xffff0000, v30
	v_add_f32_e32 v28, v28, v55
	v_lshlrev_b32_e32 v57, 16, v31
	v_add_f32_e32 v28, v28, v56
	v_and_b32_e32 v58, 0xffff0000, v31
	v_add_f32_e32 v28, v28, v57
	v_lshlrev_b32_e32 v59, 16, v32
	v_add_f32_e32 v28, v28, v58
	v_and_b32_e32 v60, 0xffff0000, v32
	v_add_f32_e32 v28, v28, v59
	v_lshlrev_b32_e32 v61, 16, v33
	v_add_f32_e32 v28, v28, v60
	v_and_b32_e32 v62, 0xffff0000, v33
	v_add_f32_e32 v28, v28, v61
	v_lshlrev_b32_e32 v63, 16, v34
	v_add_f32_e32 v28, v28, v62
	v_and_b32_e32 v64, 0xffff0000, v34
	v_add_f32_e32 v28, v28, v63
	v_lshlrev_b32_e32 v65, 16, v35
	v_add_f32_e32 v28, v28, v64
	v_and_b32_e32 v66, 0xffff0000, v35
	v_add_f32_e32 v28, v28, v65
	v_lshlrev_b32_e32 v67, 16, v36
	v_add_f32_e32 v28, v28, v66
	v_and_b32_e32 v68, 0xffff0000, v36
	v_add_f32_e32 v28, v28, v67
	v_lshlrev_b32_e32 v69, 16, v37
	v_add_f32_e32 v28, v28, v68
	v_and_b32_e32 v70, 0xffff0000, v37
	v_add_f32_e32 v28, v28, v69
	v_lshlrev_b32_e32 v71, 16, v38
	v_add_f32_e32 v28, v28, v70
	v_and_b32_e32 v72, 0xffff0000, v38
	v_add_f32_e32 v28, v28, v71
	v_lshlrev_b32_e32 v73, 16, v39
	v_add_f32_e32 v28, v28, v72
	v_and_b32_e32 v74, 0xffff0000, v39
	v_add_f32_e32 v28, v28, v73
	v_lshlrev_b32_e32 v75, 16, v40
	v_add_f32_e32 v28, v28, v74
	v_and_b32_e32 v76, 0xffff0000, v40
	v_add_f32_e32 v28, v28, v75
	v_lshlrev_b32_e32 v77, 16, v41
	v_add_f32_e32 v28, v28, v76
	v_and_b32_e32 v78, 0xffff0000, v41
	v_add_f32_e32 v28, v28, v77
	v_lshlrev_b32_e32 v47, 16, v42
	v_add_f32_e32 v28, v28, v78
	v_and_b32_e32 v46, 0xffff0000, v42
	v_add_f32_e32 v28, v28, v47
	v_lshlrev_b32_e32 v45, 16, v43
	v_add_f32_e32 v28, v28, v46
	v_and_b32_e32 v44, 0xffff0000, v43
	v_add_f32_e32 v28, v28, v45
	v_add_f32_e32 v28, v28, v44
	ds_bpermute_b32 v29, v21, v28
	s_waitcnt lgkmcnt(0)
; template <int MODE> __device__ void phase_ln(const bf16_t* src, void* dst, const float* gam, const float* bet) {
;     ...
;         float s_ = 0.f;
; #pragma unroll
;         for (int i = 0; i < 32; ++i) s_ += x[i];
;         const float mu = wave_sum(s_) * (1.0f / DM);
;         float q = 0.f;
; #pragma unroll
;         for (int i = 0; i < 32; ++i) { x[i] -= mu; q += x[i] * x[i]; }
;         const float rs = rsqrtf(wave_sum(q) * (1.0f / DM) + 1e-5f);
	v_add_f32_e32 v28, v28, v29
	ds_bpermute_b32 v29, v22, v28
	s_waitcnt lgkmcnt(0)
	v_add_f32_e32 v28, v28, v29
	ds_bpermute_b32 v29, v23, v28
	s_waitcnt lgkmcnt(0)
	v_add_f32_e32 v28, v28, v29
	ds_bpermute_b32 v29, v24, v28
	s_waitcnt lgkmcnt(0)
	v_add_f32_e32 v28, v28, v29
	ds_bpermute_b32 v29, v25, v28
	s_waitcnt lgkmcnt(0)
	v_add_f32_e32 v48, v28, v29
	ds_bpermute_b32 v49, v26, v48
	s_waitcnt lgkmcnt(0)
	v_add_f32_e32 v49, v48, v49
	v_fmac_f32_e32 v52, 0xba000000, v49
	v_fmac_f32_e32 v1, 0xba000000, v49
	v_mul_f32_e32 v79, v52, v52
	v_fmac_f32_e32 v53, 0xba000000, v49
	v_fmac_f32_e32 v79, v1, v1
	v_fmac_f32_e32 v54, 0xba000000, v49
	v_fmac_f32_e32 v79, v53, v53
	v_fmac_f32_e32 v55, 0xba000000, v49
	v_fmac_f32_e32 v79, v54, v54
	v_fmac_f32_e32 v56, 0xba000000, v49
	v_fmac_f32_e32 v79, v55, v55
	v_fmac_f32_e32 v57, 0xba000000, v49
	v_fmac_f32_e32 v79, v56, v56
	v_fmac_f32_e32 v58, 0xba000000, v49
	v_fmac_f32_e32 v79, v57, v57
	v_fmac_f32_e32 v59, 0xba000000, v49
	v_fmac_f32_e32 v79, v58, v58
	v_fmac_f32_e32 v60, 0xba000000, v49
	v_fmac_f32_e32 v79, v59, v59
	v_fmac_f32_e32 v61, 0xba000000, v49
	v_fmac_f32_e32 v79, v60, v60
	v_fmac_f32_e32 v62, 0xba000000, v49
	v_fmac_f32_e32 v79, v61, v61
	v_fmac_f32_e32 v63, 0xba000000, v49
	v_fmac_f32_e32 v79, v62, v62
	v_fmac_f32_e32 v64, 0xba000000, v49
	v_fmac_f32_e32 v79, v63, v63
	v_fmac_f32_e32 v65, 0xba000000, v49
	v_fmac_f32_e32 v79, v64, v64
	v_fmac_f32_e32 v66, 0xba000000, v49
	v_fmac_f32_e32 v79, v65, v65
	v_fmac_f32_e32 v67, 0xba000000, v49
	v_fmac_f32_e32 v79, v66, v66
	v_fmac_f32_e32 v68, 0xba000000, v49
	v_fmac_f32_e32 v79, v67, v67
	v_fmac_f32_e32 v69, 0xba000000, v49
	v_fmac_f32_e32 v79, v68, v68
	v_fmac_f32_e32 v70, 0xba000000, v49
	v_fmac_f32_e32 v79, v69, v69
	v_fmac_f32_e32 v71, 0xba000000, v49
	v_fmac_f32_e32 v79, v70, v70
	v_fmac_f32_e32 v72, 0xba000000, v49
	v_fmac_f32_e32 v79, v71, v71
	v_fmac_f32_e32 v73, 0xba000000, v49
	v_fmac_f32_e32 v79, v72, v72
	v_fmac_f32_e32 v74, 0xba000000, v49
	v_fmac_f32_e32 v79, v73, v73
	v_fmac_f32_e32 v75, 0xba000000, v49
	v_fmac_f32_e32 v79, v74, v74
	v_fmac_f32_e32 v76, 0xba000000, v49
	v_fmac_f32_e32 v79, v75, v75
	v_mul_f32_e32 v48, 0x3a000000, v49
	v_fmac_f32_e32 v77, 0xba000000, v49
	v_fmac_f32_e32 v79, v76, v76
	v_fmac_f32_e32 v78, 0xba000000, v49
	v_pk_add_f32 v[46:47], v[46:47], v[48:49] op_sel_hi:[1,0] neg_lo:[0,1] neg_hi:[0,1]
	v_fmac_f32_e32 v79, v77, v77
	v_pk_add_f32 v[44:45], v[44:45], v[48:49] op_sel_hi:[1,0] neg_lo:[0,1] neg_hi:[0,1]
	v_pk_mul_f32 v[48:49], v[46:47], v[46:47]
	v_fmac_f32_e32 v79, v78, v78
	v_add_f32_e32 v49, v49, v79
	v_pk_mul_f32 v[50:51], v[44:45], v[44:45]
	v_add_f32_e32 v48, v48, v49
	v_add_f32_e32 v48, v51, v48
	v_add_f32_e32 v48, v50, v48
	ds_bpermute_b32 v49, v21, v48
	s_waitcnt lgkmcnt(0)
	v_add_f32_e32 v48, v48, v49
	ds_bpermute_b32 v49, v22, v48
	s_waitcnt lgkmcnt(0)
	v_add_f32_e32 v48, v48, v49
	ds_bpermute_b32 v49, v23, v48
	s_waitcnt lgkmcnt(0)
	v_add_f32_e32 v48, v48, v49
	ds_bpermute_b32 v49, v24, v48
	s_waitcnt lgkmcnt(0)
	v_add_f32_e32 v48, v48, v49
	ds_bpermute_b32 v49, v25, v48
	s_waitcnt lgkmcnt(0)
	v_add_f32_e32 v48, v48, v49
	ds_bpermute_b32 v49, v26, v48
	s_waitcnt lgkmcnt(0)
; DI unsigned cvt_pk_bf16(float lo, float hi) { unsigned r; asm("v_cvt_pk_bf16_f32 %0, %1, %2" : "=v"(r) : "v"(lo), "v"(hi)); return r; }
; template <int MODE> __device__ void phase_ln(const bf16_t* src, void* dst, const float* gam, const float* bet) {
;     ...
;         const float rs = rsqrtf(wave_sum(q) * (1.0f / DM) + 1e-5f);
; #pragma unroll
;         for (int it = 0; it < 4; ++it) {
;             const int col = it * 512 + lane * 8;
;             const f32x4 g0 = *(const f32x4*)(gam + col), g1 = *(const f32x4*)(gam + col + 4), b0 = *(const f32x4*)(bet + col), b1 = *(const f32x4*)(bet + col + 4);
;             f32x4 y0, y1;
; #pragma unroll
;             for (int j = 0; j < 4; ++j) { y0[j] = x[it * 8 + j] * rs * g0[j] + b0[j]; y1[j] = x[it * 8 + 4 + j] * rs * g1[j] + b1[j]; }
;             if (MODE == 1) { float* o = (float*)dst + (size_t)row * DM + col; *(f32x4*)o = y0; *(f32x4*)(o + 4) = y1; }
;             else { u32x4 w; w.x = cvt_pk_bf16(y0[0], y0[1]); w.y = cvt_pk_bf16(y0[2], y0[3]); w.z = cvt_pk_bf16(y1[0], y1[1]); w.w = cvt_pk_bf16(y1[2], y1[3]);
;                    *(u32x4*)((bf16_t*)dst + (size_t)row * DM + col) = w; }
;         }
	v_add_f32_e32 v48, v48, v49
	v_fmamk_f32 v48, v48, 0x3a000000, v27
	v_mul_f32_e32 v49, 0x4b800000, v48
	v_cmp_gt_f32_e32 vcc, s1, v48
	s_nop 1
	v_cndmask_b32_e32 v48, v48, v49, vcc
	v_rsq_f32_e32 v48, v48
	s_nop 0
	v_mul_f32_e32 v49, 0x45800000, v48
	v_cndmask_b32_e32 v48, v48, v49, vcc
	v_mul_f32_e32 v1, v1, v48
	v_mul_f32_e32 v49, v55, v48
	v_mul_f32_e32 v50, v52, v48
	v_mul_f32_e32 v51, v56, v48
	v_mul_f32_e32 v52, v53, v48
	v_mul_f32_e32 v53, v57, v48
	v_mul_f32_e32 v54, v54, v48
	v_mul_f32_e32 v55, v58, v48
	v_mov_b64 v[28:29], v[150:151]
	v_mov_b64 v[30:31], v[152:153]
	v_mov_b64 v[32:33], v[154:155]
	v_mov_b64 v[34:35], v[156:157]
	v_mov_b64 v[36:37], v[158:159]
	v_mov_b64 v[38:39], v[160:161]
	v_mov_b64 v[40:41], v[162:163]
	v_mov_b64 v[42:43], v[164:165]
	v_fma_f32 v1, v32, v1, v40
	v_fma_f32 v32, v28, v49, v36
	v_fma_f32 v28, v33, v50, v41
	v_fma_f32 v33, v29, v51, v37
	v_fma_f32 v29, v34, v52, v42
	v_fma_f32 v34, v30, v53, v38
	v_fmac_f32_e32 v43, v35, v54
	v_fmac_f32_e32 v39, v31, v55
	v_cvt_pk_bf16_f32 v28, v1, v28
	v_cvt_pk_bf16_f32 v29, v29, v43
	v_cvt_pk_bf16_f32 v30, v32, v33
	v_cvt_pk_bf16_f32 v31, v34, v39
	global_store_dwordx4 v[18:19], v[28:31], off
	v_mul_f32_e32 v1, v59, v48
	v_mul_f32_e32 v49, v63, v48
	v_mul_f32_e32 v50, v60, v48
	v_mul_f32_e32 v51, v64, v48
	v_mul_f32_e32 v52, v61, v48
	v_mul_f32_e32 v53, v65, v48
	v_mul_f32_e32 v54, v62, v48
	v_mul_f32_e32 v55, v66, v48
	v_cmp_lt_i32_e32 vcc, s3, v0
	v_mul_f32_e32 v47, v47, v48
	v_mul_f32_e32 v46, v46, v48
	v_mul_f32_e32 v45, v45, v48
	v_mul_f32_e32 v44, v44, v48
	s_or_b64 s[8:9], vcc, s[8:9]
	v_mov_b64 v[28:29], v[166:167]
	v_mov_b64 v[30:31], v[168:169]
	v_mov_b64 v[32:33], v[170:171]
	v_mov_b64 v[34:35], v[172:173]
	v_mov_b64 v[36:37], v[174:175]
	v_mov_b64 v[38:39], v[176:177]
	v_mov_b64 v[40:41], v[178:179]
	v_mov_b64 v[42:43], v[180:181]
	v_fma_f32 v1, v32, v1, v36
	v_fma_f32 v32, v28, v49, v40
	v_fma_f32 v28, v33, v50, v37
	v_fma_f32 v33, v29, v51, v41
	v_fma_f32 v29, v34, v52, v38
	v_fma_f32 v34, v30, v53, v42
	v_fmac_f32_e32 v39, v35, v54
	v_fmac_f32_e32 v43, v31, v55
	v_cvt_pk_bf16_f32 v28, v1, v28
	v_cvt_pk_bf16_f32 v29, v29, v39
	v_cvt_pk_bf16_f32 v30, v32, v33
	v_cvt_pk_bf16_f32 v31, v34, v43
	global_store_dwordx4 v[18:19], v[28:31], off offset:1024
	v_mul_f32_e32 v1, v67, v48
	v_mul_f32_e32 v49, v71, v48
	v_mul_f32_e32 v50, v68, v48
	v_mul_f32_e32 v51, v72, v48
	v_mul_f32_e32 v52, v69, v48
	v_mul_f32_e32 v53, v73, v48
	v_mul_f32_e32 v54, v70, v48
	v_mul_f32_e32 v55, v74, v48
	v_mov_b64 v[28:29], v[182:183]
	v_mov_b64 v[30:31], v[184:185]
	v_mov_b64 v[32:33], v[186:187]
	v_mov_b64 v[34:35], v[188:189]
	v_mov_b64 v[36:37], v[190:191]
	v_mov_b64 v[38:39], v[192:193]
	v_mov_b64 v[40:41], v[194:195]
	v_mov_b64 v[42:43], v[196:197]
	v_fma_f32 v1, v32, v1, v36
	v_fma_f32 v32, v28, v49, v40
	v_fma_f32 v28, v33, v50, v37
	v_fma_f32 v33, v29, v51, v41
	v_fma_f32 v29, v34, v52, v38
	v_fma_f32 v34, v30, v53, v42
	v_fmac_f32_e32 v39, v35, v54
	v_fmac_f32_e32 v43, v31, v55
	v_cvt_pk_bf16_f32 v28, v1, v28
	v_cvt_pk_bf16_f32 v29, v29, v39
	v_cvt_pk_bf16_f32 v30, v32, v33
	v_cvt_pk_bf16_f32 v31, v34, v43
	global_store_dwordx4 v[18:19], v[28:31], off offset:2048
	v_mul_f32_e32 v1, v75, v48
	v_mul_f32_e32 v49, v76, v48
	v_mul_f32_e32 v50, v77, v48
	v_mul_f32_e32 v51, v78, v48
	v_mov_b64 v[28:29], v[198:199]
	v_mov_b64 v[30:31], v[200:201]
	v_mov_b64 v[32:33], v[202:203]
	v_mov_b64 v[34:35], v[204:205]
	v_mov_b64 v[36:37], v[206:207]
	v_mov_b64 v[38:39], v[208:209]
	v_mov_b64 v[40:41], v[210:211]
	v_mov_b64 v[42:43], v[212:213]
	v_fma_f32 v1, v32, v1, v36
	v_fma_f32 v32, v28, v47, v40
	v_fma_f32 v28, v33, v49, v37
	v_fma_f32 v33, v29, v46, v41
	v_fma_f32 v29, v34, v50, v38
	v_fma_f32 v34, v30, v45, v42
	v_fmac_f32_e32 v39, v35, v51
	v_fmac_f32_e32 v43, v31, v44
	v_cvt_pk_bf16_f32 v28, v1, v28
	v_cvt_pk_bf16_f32 v29, v29, v39
	v_cvt_pk_bf16_f32 v30, v32, v33
	v_cvt_pk_bf16_f32 v31, v34, v43
	global_store_dwordx4 v[18:19], v[28:31], off offset:3072
	s_andn2_b64 exec, exec, s[8:9]
	s_cbranch_execnz .LBB0_422
